# attention: per-tile barrier after the 2nd P.V MFMA of sub-step 1 (6 MFMAs follow the release)
# speedup vs baseline: 1.0140x; 1.0140x over previous
; __device__ __forceinline__ unsigned pk2(float lo, float hi) { return pg8::cvt_pk_bf16(lo, hi); }
; #define MFMA32(a, b, c) __builtin_amdgcn_mfma_f32_32x32x16_bf16((a), (b), (c), 0, 0, 0)
; __device__ __forceinline__ void attn_phase(const Args& a, int l, bool with_ctx, unsigned char* lds) {
;     ...
;                 for (int r = 0; r < 16; ++r) { S[r] = __builtin_amdgcn_exp2f(S[r]); ps += S[r]; }
;                 lrun += ps;
;                 u32x4 p0, p1;
;                 p0.x = pk2(S[0], S[1]); p0.y = pk2(S[2], S[3]); p0.z = pk2(S[4], S[5]); p0.w = pk2(S[6], S[7]);
;                 p1.x = pk2(S[8], S[9]); p1.y = pk2(S[10], S[11]); p1.z = pk2(S[12], S[13]); p1.w = pk2(S[14], S[15]);
;                 const bf16x8 pa0 = __builtin_bit_cast(bf16x8, p0), pa1 = __builtin_bit_cast(bf16x8, p1);
; #pragma unroll
;                 for (int j = 0; j < 4; ++j) O[j] = MFMA32(vf[2 * j], pa0, O[j]);
; #pragma unroll
;                 for (int j = 0; j < 4; ++j) O[j] = MFMA32(vf[2 * j + 1], pa1, O[j]);
;             }
;             if (t + 1 < nt) { unsigned char* kd = kdst + (cur ^ 1) * BUF; unsigned char* vd = vdst + (cur ^ 1) * BUF;
;                 *(u32x4*)kd = k0; *(u32x4*)(kd + 9216) = k1; *(u32x4*)vd = v0; *(u32x4*)(vd + 9216) = v1; }
;             __syncthreads();
.LBB0_412:
	v_exp_f32_e32 v67, v68
	v_exp_f32_e32 v68, v69
	v_exp_f32_e32 v69, v70
	v_exp_f32_e32 v70, v71
	v_exp_f32_e32 v71, v72
	v_exp_f32_e32 v72, v73
	v_exp_f32_e32 v73, v74
	v_exp_f32_e32 v74, v75
	v_cvt_pk_bf16_f32 v184, v67, v68
	v_cvt_pk_bf16_f32 v185, v69, v70
	v_cvt_pk_bf16_f32 v186, v71, v72
	v_cvt_pk_bf16_f32 v187, v73, v74
	v_exp_f32_e32 v75, v76
	v_exp_f32_e32 v76, v77
	s_waitcnt lgkmcnt(11)
	v_mfma_f32_32x32x16_bf16 v[50:65], v[136:139], v[184:187], v[50:65]
	v_exp_f32_e32 v77, v78
	v_exp_f32_e32 v78, v79
	v_exp_f32_e32 v79, v80
	v_exp_f32_e32 v80, v81
	v_exp_f32_e32 v81, v82
	v_exp_f32_e32 v82, v83
	v_cvt_pk_bf16_f32 v214, v75, v76
	s_waitcnt lgkmcnt(9)
	v_mfma_f32_32x32x16_bf16 v[34:49], v[140:143], v[184:187], v[34:49]
	s_waitcnt lgkmcnt(0)
	s_barrier
	v_cvt_pk_bf16_f32 v215, v77, v78
	v_cvt_pk_bf16_f32 v216, v79, v80
	v_cvt_pk_bf16_f32 v217, v81, v82
	s_andn2_b64 vcc, exec, s[10:11]
	s_waitcnt lgkmcnt(7)
	v_mfma_f32_32x32x16_bf16 v[18:33], v[144:147], v[184:187], v[18:33]
	s_waitcnt lgkmcnt(5)
	v_mfma_f32_32x32x16_bf16 v[2:17], v[132:135], v[184:187], v[2:17]
	v_mfma_f32_32x32x16_bf16 v[50:65], v[116:119], v[214:217], v[50:65]
	v_mfma_f32_32x32x16_bf16 v[34:49], v[120:123], v[214:217], v[34:49]
	v_mfma_f32_32x32x16_bf16 v[18:33], v[124:127], v[214:217], v[18:33]
	s_waitcnt lgkmcnt(4)
	v_mfma_f32_32x32x16_bf16 v[2:17], v[128:131], v[214:217], v[2:17]
